# attention unit epilogues (mixer C, mixer B fast path): 16 dwordx2 stores per wave widened to 8 dwordx4 via v_permlane32_swap pairs (docs 7.3); self-contained B tail
# speedup vs baseline: 1.0119x; 1.0119x over previous
; DI unsigned pack2(float lo, float hi) { f32x2_t v = {lo, hi}; return __builtin_bit_cast(unsigned, __builtin_convertvector(v, bf16x2_t)); }
; template <int MODE, int NQ, int TS, bool FAST = false> ...
;     ...
; #pragma unroll
;   for (int nq = 0; nq < NQ; ++nq) {
;     float lt = l[nq] + __shfl_xor(l[nq], 32);
;     if (MODE == 2) lt += __builtin_amdgcn_exp2f(sink2 - m2[nq]);
;     const float inv = 1.f / lt;
;     bf16_t* op = cat + (size_t)(seq_base + q0w + 32 * nq + r32) * DM + ooff + 4 * hh;
; #pragma unroll
;     for (int g = 0; g < 4; ++g) {
;       uint2 a, b;
;       a.x = pack2(o[nq][0][4 * g] * inv, o[nq][0][4 * g + 1] * inv); a.y = pack2(o[nq][0][4 * g + 2] * inv, o[nq][0][4 * g + 3] * inv);
;       b.x = pack2(o[nq][1][4 * g] * inv, o[nq][1][4 * g + 1] * inv); b.y = pack2(o[nq][1][4 * g + 2] * inv, o[nq][1][4 * g + 3] * inv);
;       *(uint2*)(op + 8 * g) = a; *(uint2*)(op + 32 + 8 * g) = b;
;     }
;   }
.LBB0_223:
	s_or_b64 exec, exec, s[0:1]
	v_xor_b32_e32 v0, 32, v223
	v_cmp_lt_i32_e32 vcc, v0, v225
	v_sub_f32_e32 v66, v183, v189
	v_exp_f32_e32 v66, v66
	v_cndmask_b32_e32 v0, v223, v0, vcc
	v_lshlrev_b32_e32 v70, 2, v0
	ds_bpermute_b32 v0, v70, v186
	s_waitcnt vmcnt(0)
	s_barrier
	s_add_i32 s5, s5, s3
	s_waitcnt lgkmcnt(0)
	v_add_f32_e32 v0, v186, v0
	v_add_f32_e32 v68, v66, v0
	ds_bpermute_b32 v78, v70, v185
	v_sub_f32_e32 v79, v183, v187
	v_exp_f32_e32 v79, v79
	v_div_scale_f32 v69, s[0:1], v68, v68, 1.0
	v_rcp_f32_e32 v71, v69
	v_lshl_add_u64 v[66:67], v[168:169], 1, s[64:65]
	v_lshlrev_b32_e32 v76, 4, v184
	v_mov_b32_e32 v77, 0
	v_lshl_add_u64 v[66:67], v[66:67], 0, v[76:77]
	v_fma_f32 v72, -v69, v71, 1.0
	v_fmac_f32_e32 v71, v72, v71
	v_div_scale_f32 v72, vcc, 1.0, v68, 1.0
	v_mul_f32_e32 v73, v72, v71
	v_fma_f32 v80, -v69, v73, v72
	v_fmac_f32_e32 v73, v80, v71
	v_fma_f32 v72, -v69, v73, v72
	v_div_fmas_f32 v72, v72, v71, v73
	v_div_fixup_f32 v74, v72, v68, 1.0
	v_lshlrev_b64 v[88:89], 11, v[170:171]
	v_lshl_add_u64 v[88:89], v[66:67], 0, v[88:89]
	v_lshlrev_b64 v[90:91], 11, v[166:167]
	v_lshl_add_u64 v[90:91], v[66:67], 0, v[90:91]
	s_waitcnt lgkmcnt(0)
	v_add_f32_e32 v82, v185, v78
	v_add_f32_e32 v82, v79, v82
	v_div_scale_f32 v83, s[0:1], v82, v82, 1.0
	v_rcp_f32_e32 v84, v83
	s_nop 0
	v_fma_f32 v85, -v83, v84, 1.0
	v_fmac_f32_e32 v84, v85, v84
	v_div_scale_f32 v85, vcc, 1.0, v82, 1.0
	v_mul_f32_e32 v86, v85, v84
	v_fma_f32 v87, -v83, v86, v85
	v_fmac_f32_e32 v86, v87, v84
	v_fma_f32 v85, -v83, v86, v85
	v_div_fmas_f32 v85, v85, v84, v86
	v_div_fixup_f32 v92, v85, v82, 1.0
	v_pk_mul_f32 v[50:51], v[50:51], v[74:75] op_sel_hi:[1,0]
	v_pk_mul_f32 v[52:53], v[52:53], v[74:75] op_sel_hi:[1,0]
	v_pk_mul_f32 v[54:55], v[54:55], v[74:75] op_sel_hi:[1,0]
	v_pk_mul_f32 v[56:57], v[56:57], v[74:75] op_sel_hi:[1,0]
	v_pk_mul_f32 v[58:59], v[58:59], v[74:75] op_sel_hi:[1,0]
	v_pk_mul_f32 v[60:61], v[60:61], v[74:75] op_sel_hi:[1,0]
	v_pk_mul_f32 v[62:63], v[62:63], v[74:75] op_sel_hi:[1,0]
	v_pk_mul_f32 v[64:65], v[64:65], v[74:75] op_sel_hi:[1,0]
	v_pk_mul_f32 v[34:35], v[34:35], v[74:75] op_sel_hi:[1,0]
	v_pk_mul_f32 v[36:37], v[36:37], v[74:75] op_sel_hi:[1,0]
	v_pk_mul_f32 v[38:39], v[38:39], v[74:75] op_sel_hi:[1,0]
	v_pk_mul_f32 v[40:41], v[40:41], v[74:75] op_sel_hi:[1,0]
	v_pk_mul_f32 v[42:43], v[42:43], v[74:75] op_sel_hi:[1,0]
	v_pk_mul_f32 v[44:45], v[44:45], v[74:75] op_sel_hi:[1,0]
	v_pk_mul_f32 v[46:47], v[46:47], v[74:75] op_sel_hi:[1,0]
	v_pk_mul_f32 v[48:49], v[48:49], v[74:75] op_sel_hi:[1,0]
	v_cvt_pk_bf16_f32 v50, v50, v51
	v_cvt_pk_bf16_f32 v51, v52, v53
	v_cvt_pk_bf16_f32 v52, v54, v55
	v_cvt_pk_bf16_f32 v53, v56, v57
	v_cvt_pk_bf16_f32 v54, v58, v59
	v_cvt_pk_bf16_f32 v55, v60, v61
	v_cvt_pk_bf16_f32 v56, v62, v63
	v_cvt_pk_bf16_f32 v57, v64, v65
	v_cvt_pk_bf16_f32 v34, v34, v35
	v_cvt_pk_bf16_f32 v35, v36, v37
	v_cvt_pk_bf16_f32 v36, v38, v39
	v_cvt_pk_bf16_f32 v37, v40, v41
	v_cvt_pk_bf16_f32 v38, v42, v43
	v_cvt_pk_bf16_f32 v39, v44, v45
	v_cvt_pk_bf16_f32 v40, v46, v47
	v_cvt_pk_bf16_f32 v41, v48, v49
	s_nop 1
	v_permlane32_swap_b32 v50, v52
	v_permlane32_swap_b32 v51, v53
	v_permlane32_swap_b32 v54, v56
	v_permlane32_swap_b32 v55, v57
	v_permlane32_swap_b32 v34, v36
	v_permlane32_swap_b32 v35, v37
	v_permlane32_swap_b32 v38, v40
	v_permlane32_swap_b32 v39, v41
	s_nop 1
	global_store_dwordx4 v[88:89], v[50:53], off
	global_store_dwordx4 v[88:89], v[54:57], off offset:32
	global_store_dwordx4 v[88:89], v[34:37], off offset:64
	global_store_dwordx4 v[88:89], v[38:41], off offset:96
	v_pk_mul_f32 v[18:19], v[18:19], v[92:93] op_sel_hi:[1,0]
	v_pk_mul_f32 v[20:21], v[20:21], v[92:93] op_sel_hi:[1,0]
	v_pk_mul_f32 v[22:23], v[22:23], v[92:93] op_sel_hi:[1,0]
	v_pk_mul_f32 v[24:25], v[24:25], v[92:93] op_sel_hi:[1,0]
	v_pk_mul_f32 v[26:27], v[26:27], v[92:93] op_sel_hi:[1,0]
	v_pk_mul_f32 v[28:29], v[28:29], v[92:93] op_sel_hi:[1,0]
	v_pk_mul_f32 v[30:31], v[30:31], v[92:93] op_sel_hi:[1,0]
	v_pk_mul_f32 v[32:33], v[32:33], v[92:93] op_sel_hi:[1,0]
	v_pk_mul_f32 v[2:3], v[2:3], v[92:93] op_sel_hi:[1,0]
	v_pk_mul_f32 v[4:5], v[4:5], v[92:93] op_sel_hi:[1,0]
	v_pk_mul_f32 v[6:7], v[6:7], v[92:93] op_sel_hi:[1,0]
	v_pk_mul_f32 v[8:9], v[8:9], v[92:93] op_sel_hi:[1,0]
	v_pk_mul_f32 v[10:11], v[10:11], v[92:93] op_sel_hi:[1,0]
	v_pk_mul_f32 v[12:13], v[12:13], v[92:93] op_sel_hi:[1,0]
	v_pk_mul_f32 v[14:15], v[14:15], v[92:93] op_sel_hi:[1,0]
	v_pk_mul_f32 v[16:17], v[16:17], v[92:93] op_sel_hi:[1,0]
	v_cvt_pk_bf16_f32 v18, v18, v19
	v_cvt_pk_bf16_f32 v19, v20, v21
	v_cvt_pk_bf16_f32 v20, v22, v23
	v_cvt_pk_bf16_f32 v21, v24, v25
	v_cvt_pk_bf16_f32 v22, v26, v27
	v_cvt_pk_bf16_f32 v23, v28, v29
	v_cvt_pk_bf16_f32 v24, v30, v31
	v_cvt_pk_bf16_f32 v25, v32, v33
	v_cvt_pk_bf16_f32 v2, v2, v3
	v_cvt_pk_bf16_f32 v3, v4, v5
	v_cvt_pk_bf16_f32 v4, v6, v7
	v_cvt_pk_bf16_f32 v5, v8, v9
	v_cvt_pk_bf16_f32 v6, v10, v11
	v_cvt_pk_bf16_f32 v7, v12, v13
	v_cvt_pk_bf16_f32 v8, v14, v15
	v_cvt_pk_bf16_f32 v9, v16, v17
	s_nop 1
	v_permlane32_swap_b32 v18, v20
	v_permlane32_swap_b32 v19, v21
	v_permlane32_swap_b32 v22, v24
	v_permlane32_swap_b32 v23, v25
	v_permlane32_swap_b32 v2, v4
	v_permlane32_swap_b32 v3, v5
	v_permlane32_swap_b32 v6, v8
	v_permlane32_swap_b32 v7, v9
	s_nop 1
	global_store_dwordx4 v[90:91], v[18:21], off
	global_store_dwordx4 v[90:91], v[22:25], off offset:32
	global_store_dwordx4 v[90:91], v[2:5], off offset:64
	global_store_dwordx4 v[90:91], v[6:9], off offset:96
	v_readlane_b32 s0, v255, 37
	s_add_i32 s4, s4, s0
	s_cmpk_lt_i32 s5, 0x400
	s_cbranch_scc0 .LBB0_245

; DI unsigned pack2(float lo, float hi) { f32x2_t v = {lo, hi}; return __builtin_bit_cast(unsigned, __builtin_convertvector(v, bf16x2_t)); }
; template <int MODE, int NQ, int TS, bool FAST = false> ...
;     ...
; #pragma unroll
;   for (int nq = 0; nq < NQ; ++nq) {
;     float lt = l[nq] + __shfl_xor(l[nq], 32);
;     if (MODE == 2) lt += __builtin_amdgcn_exp2f(sink2 - m2[nq]);
;     const float inv = 1.f / lt;
;     bf16_t* op = cat + (size_t)(seq_base + q0w + 32 * nq + r32) * DM + ooff + 4 * hh;
; #pragma unroll
;     for (int g = 0; g < 4; ++g) {
;       uint2 a, b;
;       a.x = pack2(o[nq][0][4 * g] * inv, o[nq][0][4 * g + 1] * inv); a.y = pack2(o[nq][0][4 * g + 2] * inv, o[nq][0][4 * g + 3] * inv);
;       b.x = pack2(o[nq][1][4 * g] * inv, o[nq][1][4 * g + 1] * inv); b.y = pack2(o[nq][1][4 * g + 2] * inv, o[nq][1][4 * g + 3] * inv);
;       *(uint2*)(op + 8 * g) = a; *(uint2*)(op + 32 + 8 * g) = b;
;     }
;   }
.LBB0_363:
	s_or_b64 exec, exec, s[26:27]
	ds_bpermute_b32 v68, v163, v171
	v_lshl_add_u64 v[66:67], s[64:65], 0, v[0:1]
	v_lshlrev_b32_e32 v0, 4, v182
	v_lshl_add_u64 v[66:67], v[66:67], 0, v[0:1]
	s_waitcnt vmcnt(0)
	s_barrier
	s_waitcnt lgkmcnt(0)
	v_add_f32_e32 v68, v171, v68
	ds_bpermute_b32 v78, v163, v170
	v_div_scale_f32 v69, s[4:5], v68, v68, 1.0
	v_rcp_f32_e32 v71, v69
	s_nop 0
	v_fma_f32 v72, -v69, v71, 1.0
	v_fmac_f32_e32 v71, v72, v71
	v_div_scale_f32 v72, vcc, 1.0, v68, 1.0
	v_mul_f32_e32 v73, v72, v71
	v_fma_f32 v80, -v69, v73, v72
	v_fmac_f32_e32 v73, v80, v71
	v_fma_f32 v72, -v69, v73, v72
	v_div_fmas_f32 v72, v72, v71, v73
	v_div_fixup_f32 v74, v72, v68, 1.0
	v_lshlrev_b64 v[88:89], 11, v[168:169]
	v_lshl_add_u64 v[88:89], v[66:67], 0, v[88:89]
	v_lshlrev_b64 v[90:91], 11, v[166:167]
	v_lshl_add_u64 v[90:91], v[66:67], 0, v[90:91]
	s_waitcnt lgkmcnt(0)
	v_add_f32_e32 v82, v170, v78
	v_div_scale_f32 v83, s[4:5], v82, v82, 1.0
	v_rcp_f32_e32 v84, v83
	s_nop 0
	v_fma_f32 v85, -v83, v84, 1.0
	v_fmac_f32_e32 v84, v85, v84
	v_div_scale_f32 v85, vcc, 1.0, v82, 1.0
	v_mul_f32_e32 v86, v85, v84
	v_fma_f32 v87, -v83, v86, v85
	v_fmac_f32_e32 v86, v87, v84
	v_fma_f32 v85, -v83, v86, v85
	v_div_fmas_f32 v85, v85, v84, v86
	v_div_fixup_f32 v92, v85, v82, 1.0
	v_pk_mul_f32 v[50:51], v[50:51], v[74:75] op_sel_hi:[1,0]
	v_pk_mul_f32 v[52:53], v[52:53], v[74:75] op_sel_hi:[1,0]
	v_pk_mul_f32 v[54:55], v[54:55], v[74:75] op_sel_hi:[1,0]
	v_pk_mul_f32 v[56:57], v[56:57], v[74:75] op_sel_hi:[1,0]
	v_pk_mul_f32 v[58:59], v[58:59], v[74:75] op_sel_hi:[1,0]
	v_pk_mul_f32 v[60:61], v[60:61], v[74:75] op_sel_hi:[1,0]
	v_pk_mul_f32 v[62:63], v[62:63], v[74:75] op_sel_hi:[1,0]
	v_pk_mul_f32 v[64:65], v[64:65], v[74:75] op_sel_hi:[1,0]
	v_pk_mul_f32 v[34:35], v[34:35], v[74:75] op_sel_hi:[1,0]
	v_pk_mul_f32 v[36:37], v[36:37], v[74:75] op_sel_hi:[1,0]
	v_pk_mul_f32 v[38:39], v[38:39], v[74:75] op_sel_hi:[1,0]
	v_pk_mul_f32 v[40:41], v[40:41], v[74:75] op_sel_hi:[1,0]
	v_pk_mul_f32 v[42:43], v[42:43], v[74:75] op_sel_hi:[1,0]
	v_pk_mul_f32 v[44:45], v[44:45], v[74:75] op_sel_hi:[1,0]
	v_pk_mul_f32 v[46:47], v[46:47], v[74:75] op_sel_hi:[1,0]
	v_pk_mul_f32 v[48:49], v[48:49], v[74:75] op_sel_hi:[1,0]
	v_cvt_pk_bf16_f32 v50, v50, v51
	v_cvt_pk_bf16_f32 v51, v52, v53
	v_cvt_pk_bf16_f32 v52, v54, v55
	v_cvt_pk_bf16_f32 v53, v56, v57
	v_cvt_pk_bf16_f32 v54, v58, v59
	v_cvt_pk_bf16_f32 v55, v60, v61
	v_cvt_pk_bf16_f32 v56, v62, v63
	v_cvt_pk_bf16_f32 v57, v64, v65
	v_cvt_pk_bf16_f32 v34, v34, v35
	v_cvt_pk_bf16_f32 v35, v36, v37
	v_cvt_pk_bf16_f32 v36, v38, v39
	v_cvt_pk_bf16_f32 v37, v40, v41
	v_cvt_pk_bf16_f32 v38, v42, v43
	v_cvt_pk_bf16_f32 v39, v44, v45
	v_cvt_pk_bf16_f32 v40, v46, v47
	v_cvt_pk_bf16_f32 v41, v48, v49
	s_nop 1
	v_permlane32_swap_b32 v50, v52
	v_permlane32_swap_b32 v51, v53
	v_permlane32_swap_b32 v54, v56
	v_permlane32_swap_b32 v55, v57
	v_permlane32_swap_b32 v34, v36
	v_permlane32_swap_b32 v35, v37
	v_permlane32_swap_b32 v38, v40
	v_permlane32_swap_b32 v39, v41
	s_nop 1
	global_store_dwordx4 v[88:89], v[50:53], off offset:1024
	global_store_dwordx4 v[88:89], v[54:57], off offset:1056
	global_store_dwordx4 v[88:89], v[34:37], off offset:1088
	global_store_dwordx4 v[88:89], v[38:41], off offset:1120
	v_pk_mul_f32 v[18:19], v[18:19], v[92:93] op_sel_hi:[1,0]
	v_pk_mul_f32 v[20:21], v[20:21], v[92:93] op_sel_hi:[1,0]
	v_pk_mul_f32 v[22:23], v[22:23], v[92:93] op_sel_hi:[1,0]
	v_pk_mul_f32 v[24:25], v[24:25], v[92:93] op_sel_hi:[1,0]
	v_pk_mul_f32 v[26:27], v[26:27], v[92:93] op_sel_hi:[1,0]
	v_pk_mul_f32 v[28:29], v[28:29], v[92:93] op_sel_hi:[1,0]
	v_pk_mul_f32 v[30:31], v[30:31], v[92:93] op_sel_hi:[1,0]
	v_pk_mul_f32 v[32:33], v[32:33], v[92:93] op_sel_hi:[1,0]
	v_pk_mul_f32 v[2:3], v[2:3], v[92:93] op_sel_hi:[1,0]
	v_pk_mul_f32 v[4:5], v[4:5], v[92:93] op_sel_hi:[1,0]
	v_pk_mul_f32 v[6:7], v[6:7], v[92:93] op_sel_hi:[1,0]
	v_pk_mul_f32 v[8:9], v[8:9], v[92:93] op_sel_hi:[1,0]
	v_pk_mul_f32 v[10:11], v[10:11], v[92:93] op_sel_hi:[1,0]
	v_pk_mul_f32 v[12:13], v[12:13], v[92:93] op_sel_hi:[1,0]
	v_pk_mul_f32 v[14:15], v[14:15], v[92:93] op_sel_hi:[1,0]
	v_pk_mul_f32 v[16:17], v[16:17], v[92:93] op_sel_hi:[1,0]
	v_cvt_pk_bf16_f32 v18, v18, v19
	v_cvt_pk_bf16_f32 v19, v20, v21
	v_cvt_pk_bf16_f32 v20, v22, v23
	v_cvt_pk_bf16_f32 v21, v24, v25
	v_cvt_pk_bf16_f32 v22, v26, v27
	v_cvt_pk_bf16_f32 v23, v28, v29
	v_cvt_pk_bf16_f32 v24, v30, v31
	v_cvt_pk_bf16_f32 v25, v32, v33
	v_cvt_pk_bf16_f32 v2, v2, v3
	v_cvt_pk_bf16_f32 v3, v4, v5
	v_cvt_pk_bf16_f32 v4, v6, v7
	v_cvt_pk_bf16_f32 v5, v8, v9
	v_cvt_pk_bf16_f32 v6, v10, v11
	v_cvt_pk_bf16_f32 v7, v12, v13
	v_cvt_pk_bf16_f32 v8, v14, v15
	v_cvt_pk_bf16_f32 v9, v16, v17
	s_nop 1
	v_permlane32_swap_b32 v18, v20
	v_permlane32_swap_b32 v19, v21
	v_permlane32_swap_b32 v22, v24
	v_permlane32_swap_b32 v23, v25
	v_permlane32_swap_b32 v2, v4
	v_permlane32_swap_b32 v3, v5
	v_permlane32_swap_b32 v6, v8
	v_permlane32_swap_b32 v7, v9
	s_nop 1
	global_store_dwordx4 v[90:91], v[18:21], off offset:1024
	global_store_dwordx4 v[90:91], v[22:25], off offset:1056
	global_store_dwordx4 v[90:91], v[2:5], off offset:1088
	global_store_dwordx4 v[90:91], v[6:9], off offset:1120
	s_or_b64 exec, exec, s[0:1]
	v_readlane_b32 s0, v255, 39
	s_add_i32 s81, s81, s3
	s_add_i32 s80, s80, s0
	s_cmpk_gt_i32 s81, 0x5ff
	s_cbranch_scc1 .LBB0_447
	s_branch .LBB0_366
